# RWKV scan compute loop hand-pipelined: LDS reads 2 steps ahead into a 3-deep register ring with one counted lgkmcnt per step (was lgkmcnt(0) right after issue)
# speedup vs baseline: 1.0220x; 1.0137x over previous
; #define LAUNDER_V(x) asm volatile("" : "+v"(x))
; template <int CTRL> __device__ __forceinline__ float dpp_add(float x) { const int y = __builtin_amdgcn_update_dpp(0, __float_as_int(x), CTRL, 0xf, 0xf, false); return x + __int_as_float(y); }
; #define LO2(x) __builtin_shufflevector(x, x, 0, 1)
; #define HI2(x) __builtin_shufflevector(x, x, 2, 3)
; template <int DIR> __device__ __forceinline__ void rwkv_scan_dir(const Params& P, unsigned char* lds, int sb, int tid) {
;     ...
;             const float* rp = buf + (ck % SC_NB) * SC_BUF + 4 * j;
;             const float* vp = buf + (ck % SC_NB) * SC_BUF + 320 + rowi;
;             int yoff = (ck & 1) * SC_YP + rowi * 4 + (j & 3); LAUNDER_V(yoff);
;             float* yp = ypart + yoff;
;             f32x4 w = *(const f32x4*)(rp), kk = *(const f32x4*)(rp + 64), kka = *(const f32x4*)(rp + 128), km = *(const f32x4*)(rp + 192), r = *(const f32x4*)(rp + 256);
;             float v = *vp;
;             f32x4 w1 = *(const f32x4*)(rp + 336), kk1 = *(const f32x4*)(rp + 336 + 64), kka1 = *(const f32x4*)(rp + 336 + 128), km1 = *(const f32x4*)(rp + 336 + 192), r1 = *(const f32x4*)(rp + 336 + 256);
;             float v1 = vp[336];
;     ...
; #pragma unroll 8
;             for (int st = 0; st < SC_CH; ++st) {
;                 const float* rn = rp + (st + 2) * 336;
;                 const f32x4 nw = *(const f32x4*)(rn), nkk = *(const f32x4*)(rn + 64), nkka = *(const f32x4*)(rn + 128), nkm = *(const f32x4*)(rn + 192), nr = *(const f32x4*)(rn + 256);
;                 const float nv = vp[(st + 2) * 336];
;                 f32x2 q = sA * LO2(kk); q = sB * HI2(kk) + q;
;                 float sk = q.x + q.y;
;                 float yy = 0.f;
;                 if (DIR == 1) { f32x2 yq = sA * LO2(r); yq = sB * HI2(r) + yq; yy = yq.x + yq.y; }
;                 sk = row16_sum(sk);
;                 f32x2 tA = LO2(km) * v, tB = HI2(km) * v;
;                 tA = sA * LO2(w) + tA; tB = sB * HI2(w) + tB;
;                 sA = LO2(kka) * sk + tA; sB = HI2(kka) * sk + tB;
;                 if (DIR == 0) { f32x2 yq = sA * LO2(r); yq = sB * HI2(r) + yq; yy = yq.x + yq.y; }
;                 yy = dpp_add<0x128>(yy); yy = dpp_add<0x124>(yy);
;                 yp[st * 64] = yy;
;                 w = w1; kk = kk1; kka = kka1; km = km1; r = r1; v = v1;
;                 w1 = nw; kk1 = nkk; kka1 = nkka; km1 = nkm; r1 = nr; v1 = nv;
;             }
.LBB0_74:
	s_and_saveexec_b64 s[10:11], s[4:5]
	s_xor_b64 s[10:11], exec, s[10:11]
	s_cbranch_execz .LBB0_78
	s_waitcnt lgkmcnt(0)
	v_mul_u32_u24_e32 v118, 0xcd, v185
	v_lshrrev_b32_e32 v118, 10, v118
	v_mul_u32_u24_e32 v119, 5, v118
	v_sub_u32_e32 v118, v185, v119
	v_mul_u32_u24_e32 v119, 0x5400, v118
	v_lshl_add_u32 v186, v156, 2, v119
	v_lshl_add_u32 v187, v184, 2, v119
	ds_read_b128 v[0:3], v186 offset:0
	ds_read_b128 v[4:7], v186 offset:256
	ds_read_b128 v[8:11], v186 offset:512
	ds_read_b128 v[12:15], v186 offset:768
	ds_read_b128 v[16:19], v186 offset:1024
	ds_read_b32 v20, v187 offset:1280
	ds_read_b128 v[22:25], v186 offset:1344
	ds_read_b128 v[26:29], v186 offset:1600
	ds_read_b128 v[30:33], v186 offset:1856
	ds_read_b128 v[34:37], v186 offset:2112
	ds_read_b128 v[38:41], v186 offset:2368
	ds_read_b32 v42, v187 offset:2624
	v_lshlrev_b32_e32 v189, 10, v185
	v_and_b32_e32 v189, 0x400, v189
	v_or_b32_e32 v189, v189, v125
	v_lshlrev_b32_e32 v189, 2, v189
	v_add_u32_e32 v189, 0x1b400, v189
	s_waitcnt lgkmcnt(6)
	v_pk_mul_f32 v[92:93], v[144:145], v[4:5]
	v_pk_mul_f32 v[96:97], v[12:13], v[20:21] op_sel_hi:[1,0]
	v_pk_fma_f32 v[92:93], v[146:147], v[6:7], v[92:93]
	v_pk_mul_f32 v[98:99], v[14:15], v[20:21] op_sel_hi:[1,0]
	s_nop 0
	v_add_f32_e32 v92, v92, v93
	v_pk_fma_f32 v[96:97], v[144:145], v[0:1], v[96:97]
	v_pk_fma_f32 v[98:99], v[146:147], v[2:3], v[98:99]
	v_add_f32_dpp v92, v92, v92 row_ror:8 row_mask:0xf bank_mask:0xf bound_ctrl:1
	s_nop 0
	ds_read_b128 v[44:47], v186 offset:2688
	v_add_f32_dpp v92, v92, v92 row_ror:4 row_mask:0xf bank_mask:0xf bound_ctrl:1
	ds_read_b128 v[48:51], v186 offset:2944
	ds_read_b128 v[52:55], v186 offset:3200
	v_add_f32_dpp v92, v92, v92 row_ror:2 row_mask:0xf bank_mask:0xf bound_ctrl:1
	s_nop 0
	ds_read_b128 v[56:59], v186 offset:3456
	v_add_f32_dpp v92, v92, v92 row_ror:1 row_mask:0xf bank_mask:0xf bound_ctrl:1
	ds_read_b128 v[60:63], v186 offset:3712
	ds_read_b32 v64, v187 offset:3968
	v_pk_fma_f32 v[144:145], v[8:9], v[92:93], v[96:97] op_sel_hi:[1,0,1]
	v_pk_fma_f32 v[146:147], v[10:11], v[92:93], v[98:99] op_sel_hi:[1,0,1]
	v_pk_mul_f32 v[100:101], v[144:145], v[16:17]
	v_pk_fma_f32 v[100:101], v[146:147], v[18:19], v[100:101]
	s_waitcnt lgkmcnt(6)
	v_pk_mul_f32 v[92:93], v[144:145], v[26:27]
	v_pk_mul_f32 v[96:97], v[34:35], v[42:43] op_sel_hi:[1,0]
	v_pk_fma_f32 v[92:93], v[146:147], v[28:29], v[92:93]
	v_pk_mul_f32 v[98:99], v[36:37], v[42:43] op_sel_hi:[1,0]
	v_add_f32_e32 v100, v100, v101
	v_add_f32_e32 v92, v92, v93
	v_pk_fma_f32 v[96:97], v[144:145], v[22:23], v[96:97]
	v_pk_fma_f32 v[98:99], v[146:147], v[24:25], v[98:99]
	v_add_f32_dpp v92, v92, v92 row_ror:8 row_mask:0xf bank_mask:0xf bound_ctrl:1
	v_add_f32_dpp v100, v100, v100 row_ror:8 row_mask:0xf bank_mask:0xf bound_ctrl:1
	ds_read_b128 v[0:3], v186 offset:4032
	v_add_f32_dpp v92, v92, v92 row_ror:4 row_mask:0xf bank_mask:0xf bound_ctrl:1
	ds_read_b128 v[4:7], v186 offset:4288
	ds_read_b128 v[8:11], v186 offset:4544
	v_add_f32_dpp v92, v92, v92 row_ror:2 row_mask:0xf bank_mask:0xf bound_ctrl:1
	v_add_f32_dpp v100, v100, v100 row_ror:4 row_mask:0xf bank_mask:0xf bound_ctrl:1
	ds_read_b128 v[12:15], v186 offset:4800
	v_add_f32_dpp v92, v92, v92 row_ror:1 row_mask:0xf bank_mask:0xf bound_ctrl:1
	ds_read_b128 v[16:19], v186 offset:5056
	ds_read_b32 v20, v187 offset:5312
	v_pk_fma_f32 v[144:145], v[30:31], v[92:93], v[96:97] op_sel_hi:[1,0,1]
	v_pk_fma_f32 v[146:147], v[32:33], v[92:93], v[98:99] op_sel_hi:[1,0,1]
	ds_write_b32 v189, v100 offset:0
	v_pk_mul_f32 v[102:103], v[144:145], v[38:39]
	v_pk_fma_f32 v[102:103], v[146:147], v[40:41], v[102:103]
	s_waitcnt lgkmcnt(7)
	v_pk_mul_f32 v[92:93], v[144:145], v[48:49]
	v_pk_mul_f32 v[96:97], v[56:57], v[64:65] op_sel_hi:[1,0]
	v_pk_fma_f32 v[92:93], v[146:147], v[50:51], v[92:93]
	v_pk_mul_f32 v[98:99], v[58:59], v[64:65] op_sel_hi:[1,0]
	v_add_f32_e32 v102, v102, v103
	v_add_f32_e32 v92, v92, v93
	v_pk_fma_f32 v[96:97], v[144:145], v[44:45], v[96:97]
	v_pk_fma_f32 v[98:99], v[146:147], v[46:47], v[98:99]
	v_add_f32_dpp v92, v92, v92 row_ror:8 row_mask:0xf bank_mask:0xf bound_ctrl:1
	v_add_f32_dpp v102, v102, v102 row_ror:8 row_mask:0xf bank_mask:0xf bound_ctrl:1
	ds_read_b128 v[22:25], v186 offset:5376
	v_add_f32_dpp v92, v92, v92 row_ror:4 row_mask:0xf bank_mask:0xf bound_ctrl:1
	ds_read_b128 v[26:29], v186 offset:5632
	ds_read_b128 v[30:33], v186 offset:5888
	v_add_f32_dpp v92, v92, v92 row_ror:2 row_mask:0xf bank_mask:0xf bound_ctrl:1
	v_add_f32_dpp v102, v102, v102 row_ror:4 row_mask:0xf bank_mask:0xf bound_ctrl:1
	ds_read_b128 v[34:37], v186 offset:6144
	v_add_f32_dpp v92, v92, v92 row_ror:1 row_mask:0xf bank_mask:0xf bound_ctrl:1
	ds_read_b128 v[38:41], v186 offset:6400
	ds_read_b32 v42, v187 offset:6656
	v_pk_fma_f32 v[144:145], v[52:53], v[92:93], v[96:97] op_sel_hi:[1,0,1]
	v_pk_fma_f32 v[146:147], v[54:55], v[92:93], v[98:99] op_sel_hi:[1,0,1]
	ds_write_b32 v189, v102 offset:256
	v_pk_mul_f32 v[100:101], v[144:145], v[60:61]
	v_pk_fma_f32 v[100:101], v[146:147], v[62:63], v[100:101]
	s_waitcnt lgkmcnt(8)
; template <int CTRL> __device__ __forceinline__ float dpp_add(float x) { const int y = __builtin_amdgcn_update_dpp(0, __float_as_int(x), CTRL, 0xf, 0xf, false); return x + __int_as_float(y); }
; __device__ __forceinline__ float row16_sum(float x) { x = dpp_add<0x128>(x); x = dpp_add<0x124>(x); x = dpp_add<0x122>(x); x = dpp_add<0x121>(x); return x; }
; #define LO2(x) __builtin_shufflevector(x, x, 0, 1)
; #define HI2(x) __builtin_shufflevector(x, x, 2, 3)
; template <int DIR> __device__ __forceinline__ void rwkv_scan_dir(const Params& P, unsigned char* lds, int sb, int tid) {
;     ...
;             for (int st = 0; st < SC_CH; ++st) {
;                 const float* rn = rp + (st + 2) * 336;
;                 const f32x4 nw = *(const f32x4*)(rn), nkk = *(const f32x4*)(rn + 64), nkka = *(const f32x4*)(rn + 128), nkm = *(const f32x4*)(rn + 192), nr = *(const f32x4*)(rn + 256);
;                 const float nv = vp[(st + 2) * 336];
;                 f32x2 q = sA * LO2(kk); q = sB * HI2(kk) + q;
;                 float sk = q.x + q.y;
;                 float yy = 0.f;
;                 if (DIR == 1) { f32x2 yq = sA * LO2(r); yq = sB * HI2(r) + yq; yy = yq.x + yq.y; }
;                 sk = row16_sum(sk);
;                 f32x2 tA = LO2(km) * v, tB = HI2(km) * v;
;                 tA = sA * LO2(w) + tA; tB = sB * HI2(w) + tB;
;                 sA = LO2(kka) * sk + tA; sB = HI2(kka) * sk + tB;
;                 if (DIR == 0) { f32x2 yq = sA * LO2(r); yq = sB * HI2(r) + yq; yy = yq.x + yq.y; }
;                 yy = dpp_add<0x128>(yy); yy = dpp_add<0x124>(yy);
;                 yp[st * 64] = yy;
;                 w = w1; kk = kk1; kka = kka1; km = km1; r = r1; v = v1;
;                 w1 = nw; kk1 = nkk; kka1 = nkka; km1 = nkm; r1 = nr; v1 = nv;
;             }
	v_pk_mul_f32 v[92:93], v[144:145], v[4:5]
	v_pk_mul_f32 v[96:97], v[12:13], v[20:21] op_sel_hi:[1,0]
	v_pk_fma_f32 v[92:93], v[146:147], v[6:7], v[92:93]
	v_pk_mul_f32 v[98:99], v[14:15], v[20:21] op_sel_hi:[1,0]
	v_add_f32_e32 v100, v100, v101
	v_add_f32_e32 v92, v92, v93
	v_pk_fma_f32 v[96:97], v[144:145], v[0:1], v[96:97]
	v_pk_fma_f32 v[98:99], v[146:147], v[2:3], v[98:99]
	v_add_f32_dpp v92, v92, v92 row_ror:8 row_mask:0xf bank_mask:0xf bound_ctrl:1
	v_add_f32_dpp v100, v100, v100 row_ror:8 row_mask:0xf bank_mask:0xf bound_ctrl:1
	ds_read_b128 v[44:47], v186 offset:6720
	v_add_f32_dpp v92, v92, v92 row_ror:4 row_mask:0xf bank_mask:0xf bound_ctrl:1
	ds_read_b128 v[48:51], v186 offset:6976
	ds_read_b128 v[52:55], v186 offset:7232
	v_add_f32_dpp v92, v92, v92 row_ror:2 row_mask:0xf bank_mask:0xf bound_ctrl:1
	v_add_f32_dpp v100, v100, v100 row_ror:4 row_mask:0xf bank_mask:0xf bound_ctrl:1
	ds_read_b128 v[56:59], v186 offset:7488
	v_add_f32_dpp v92, v92, v92 row_ror:1 row_mask:0xf bank_mask:0xf bound_ctrl:1
	ds_read_b128 v[60:63], v186 offset:7744
	ds_read_b32 v64, v187 offset:8000
	v_pk_fma_f32 v[144:145], v[8:9], v[92:93], v[96:97] op_sel_hi:[1,0,1]
	v_pk_fma_f32 v[146:147], v[10:11], v[92:93], v[98:99] op_sel_hi:[1,0,1]
	ds_write_b32 v189, v100 offset:512
	v_pk_mul_f32 v[102:103], v[144:145], v[16:17]
	v_pk_fma_f32 v[102:103], v[146:147], v[18:19], v[102:103]
	s_waitcnt lgkmcnt(8)
	v_pk_mul_f32 v[92:93], v[144:145], v[26:27]
	v_pk_mul_f32 v[96:97], v[34:35], v[42:43] op_sel_hi:[1,0]
	v_pk_fma_f32 v[92:93], v[146:147], v[28:29], v[92:93]
	v_pk_mul_f32 v[98:99], v[36:37], v[42:43] op_sel_hi:[1,0]
	v_add_f32_e32 v102, v102, v103
	v_add_f32_e32 v92, v92, v93
	v_pk_fma_f32 v[96:97], v[144:145], v[22:23], v[96:97]
	v_pk_fma_f32 v[98:99], v[146:147], v[24:25], v[98:99]
	v_add_f32_dpp v92, v92, v92 row_ror:8 row_mask:0xf bank_mask:0xf bound_ctrl:1
	v_add_f32_dpp v102, v102, v102 row_ror:8 row_mask:0xf bank_mask:0xf bound_ctrl:1
	ds_read_b128 v[0:3], v186 offset:8064
	v_add_f32_dpp v92, v92, v92 row_ror:4 row_mask:0xf bank_mask:0xf bound_ctrl:1
	ds_read_b128 v[4:7], v186 offset:8320
	ds_read_b128 v[8:11], v186 offset:8576
	v_add_f32_dpp v92, v92, v92 row_ror:2 row_mask:0xf bank_mask:0xf bound_ctrl:1
	v_add_f32_dpp v102, v102, v102 row_ror:4 row_mask:0xf bank_mask:0xf bound_ctrl:1
	ds_read_b128 v[12:15], v186 offset:8832
	v_add_f32_dpp v92, v92, v92 row_ror:1 row_mask:0xf bank_mask:0xf bound_ctrl:1
	ds_read_b128 v[16:19], v186 offset:9088
	ds_read_b32 v20, v187 offset:9344
	v_pk_fma_f32 v[144:145], v[30:31], v[92:93], v[96:97] op_sel_hi:[1,0,1]
	v_pk_fma_f32 v[146:147], v[32:33], v[92:93], v[98:99] op_sel_hi:[1,0,1]
	ds_write_b32 v189, v102 offset:768
	v_pk_mul_f32 v[100:101], v[144:145], v[38:39]
	v_pk_fma_f32 v[100:101], v[146:147], v[40:41], v[100:101]
	s_waitcnt lgkmcnt(8)
	v_pk_mul_f32 v[92:93], v[144:145], v[48:49]
	v_pk_mul_f32 v[96:97], v[56:57], v[64:65] op_sel_hi:[1,0]
	v_pk_fma_f32 v[92:93], v[146:147], v[50:51], v[92:93]
	v_pk_mul_f32 v[98:99], v[58:59], v[64:65] op_sel_hi:[1,0]
	v_add_f32_e32 v100, v100, v101
	v_add_f32_e32 v92, v92, v93
	v_pk_fma_f32 v[96:97], v[144:145], v[44:45], v[96:97]
	v_pk_fma_f32 v[98:99], v[146:147], v[46:47], v[98:99]
	v_add_f32_dpp v92, v92, v92 row_ror:8 row_mask:0xf bank_mask:0xf bound_ctrl:1
	v_add_f32_dpp v100, v100, v100 row_ror:8 row_mask:0xf bank_mask:0xf bound_ctrl:1
	ds_read_b128 v[22:25], v186 offset:9408
	v_add_f32_dpp v92, v92, v92 row_ror:4 row_mask:0xf bank_mask:0xf bound_ctrl:1
	ds_read_b128 v[26:29], v186 offset:9664
	ds_read_b128 v[30:33], v186 offset:9920
	v_add_f32_dpp v92, v92, v92 row_ror:2 row_mask:0xf bank_mask:0xf bound_ctrl:1
	v_add_f32_dpp v100, v100, v100 row_ror:4 row_mask:0xf bank_mask:0xf bound_ctrl:1
	ds_read_b128 v[34:37], v186 offset:10176
	v_add_f32_dpp v92, v92, v92 row_ror:1 row_mask:0xf bank_mask:0xf bound_ctrl:1
	ds_read_b128 v[38:41], v186 offset:10432
	ds_read_b32 v42, v187 offset:10688
	v_pk_fma_f32 v[144:145], v[52:53], v[92:93], v[96:97] op_sel_hi:[1,0,1]
	v_pk_fma_f32 v[146:147], v[54:55], v[92:93], v[98:99] op_sel_hi:[1,0,1]
	ds_write_b32 v189, v100 offset:1024
	v_pk_mul_f32 v[102:103], v[144:145], v[60:61]
	v_pk_fma_f32 v[102:103], v[146:147], v[62:63], v[102:103]
	s_waitcnt lgkmcnt(8)
	v_pk_mul_f32 v[92:93], v[144:145], v[4:5]
	v_pk_mul_f32 v[96:97], v[12:13], v[20:21] op_sel_hi:[1,0]
	v_pk_fma_f32 v[92:93], v[146:147], v[6:7], v[92:93]
	v_pk_mul_f32 v[98:99], v[14:15], v[20:21] op_sel_hi:[1,0]
	v_add_f32_e32 v102, v102, v103
	v_add_f32_e32 v92, v92, v93
	v_pk_fma_f32 v[96:97], v[144:145], v[0:1], v[96:97]
	v_pk_fma_f32 v[98:99], v[146:147], v[2:3], v[98:99]
	v_add_f32_dpp v92, v92, v92 row_ror:8 row_mask:0xf bank_mask:0xf bound_ctrl:1
	v_add_f32_dpp v102, v102, v102 row_ror:8 row_mask:0xf bank_mask:0xf bound_ctrl:1
	ds_read_b128 v[44:47], v186 offset:10752
	v_add_f32_dpp v92, v92, v92 row_ror:4 row_mask:0xf bank_mask:0xf bound_ctrl:1
	ds_read_b128 v[48:51], v186 offset:11008
	ds_read_b128 v[52:55], v186 offset:11264
	v_add_f32_dpp v92, v92, v92 row_ror:2 row_mask:0xf bank_mask:0xf bound_ctrl:1
	v_add_f32_dpp v102, v102, v102 row_ror:4 row_mask:0xf bank_mask:0xf bound_ctrl:1
	ds_read_b128 v[56:59], v186 offset:11520
	v_add_f32_dpp v92, v92, v92 row_ror:1 row_mask:0xf bank_mask:0xf bound_ctrl:1
	ds_read_b128 v[60:63], v186 offset:11776
	ds_read_b32 v64, v187 offset:12032
	v_pk_fma_f32 v[144:145], v[8:9], v[92:93], v[96:97] op_sel_hi:[1,0,1]
	v_pk_fma_f32 v[146:147], v[10:11], v[92:93], v[98:99] op_sel_hi:[1,0,1]
	ds_write_b32 v189, v102 offset:1280
	v_pk_mul_f32 v[100:101], v[144:145], v[16:17]
	v_pk_fma_f32 v[100:101], v[146:147], v[18:19], v[100:101]
	s_waitcnt lgkmcnt(8)
; template <int CTRL> __device__ __forceinline__ float dpp_add(float x) { const int y = __builtin_amdgcn_update_dpp(0, __float_as_int(x), CTRL, 0xf, 0xf, false); return x + __int_as_float(y); }
; __device__ __forceinline__ float row16_sum(float x) { x = dpp_add<0x128>(x); x = dpp_add<0x124>(x); x = dpp_add<0x122>(x); x = dpp_add<0x121>(x); return x; }
; #define LO2(x) __builtin_shufflevector(x, x, 0, 1)
; #define HI2(x) __builtin_shufflevector(x, x, 2, 3)
; template <int DIR> __device__ __forceinline__ void rwkv_scan_dir(const Params& P, unsigned char* lds, int sb, int tid) {
;     ...
;             for (int st = 0; st < SC_CH; ++st) {
;                 const float* rn = rp + (st + 2) * 336;
;                 const f32x4 nw = *(const f32x4*)(rn), nkk = *(const f32x4*)(rn + 64), nkka = *(const f32x4*)(rn + 128), nkm = *(const f32x4*)(rn + 192), nr = *(const f32x4*)(rn + 256);
;                 const float nv = vp[(st + 2) * 336];
;                 f32x2 q = sA * LO2(kk); q = sB * HI2(kk) + q;
;                 float sk = q.x + q.y;
;                 float yy = 0.f;
;                 if (DIR == 1) { f32x2 yq = sA * LO2(r); yq = sB * HI2(r) + yq; yy = yq.x + yq.y; }
;                 sk = row16_sum(sk);
;                 f32x2 tA = LO2(km) * v, tB = HI2(km) * v;
;                 tA = sA * LO2(w) + tA; tB = sB * HI2(w) + tB;
;                 sA = LO2(kka) * sk + tA; sB = HI2(kka) * sk + tB;
;                 if (DIR == 0) { f32x2 yq = sA * LO2(r); yq = sB * HI2(r) + yq; yy = yq.x + yq.y; }
;                 yy = dpp_add<0x128>(yy); yy = dpp_add<0x124>(yy);
;                 yp[st * 64] = yy;
;                 w = w1; kk = kk1; kka = kka1; km = km1; r = r1; v = v1;
;                 w1 = nw; kk1 = nkk; kka1 = nkka; km1 = nkm; r1 = nr; v1 = nv;
	v_pk_mul_f32 v[92:93], v[144:145], v[26:27]
	v_pk_mul_f32 v[96:97], v[34:35], v[42:43] op_sel_hi:[1,0]
	v_pk_fma_f32 v[92:93], v[146:147], v[28:29], v[92:93]
	v_pk_mul_f32 v[98:99], v[36:37], v[42:43] op_sel_hi:[1,0]
	v_add_f32_e32 v100, v100, v101
	v_add_f32_e32 v92, v92, v93
	v_pk_fma_f32 v[96:97], v[144:145], v[22:23], v[96:97]
	v_pk_fma_f32 v[98:99], v[146:147], v[24:25], v[98:99]
	v_add_f32_dpp v92, v92, v92 row_ror:8 row_mask:0xf bank_mask:0xf bound_ctrl:1
	v_add_f32_dpp v100, v100, v100 row_ror:8 row_mask:0xf bank_mask:0xf bound_ctrl:1
	ds_read_b128 v[0:3], v186 offset:12096
	v_add_f32_dpp v92, v92, v92 row_ror:4 row_mask:0xf bank_mask:0xf bound_ctrl:1
	ds_read_b128 v[4:7], v186 offset:12352
	ds_read_b128 v[8:11], v186 offset:12608
	v_add_f32_dpp v92, v92, v92 row_ror:2 row_mask:0xf bank_mask:0xf bound_ctrl:1
	v_add_f32_dpp v100, v100, v100 row_ror:4 row_mask:0xf bank_mask:0xf bound_ctrl:1
	ds_read_b128 v[12:15], v186 offset:12864
	v_add_f32_dpp v92, v92, v92 row_ror:1 row_mask:0xf bank_mask:0xf bound_ctrl:1
	ds_read_b128 v[16:19], v186 offset:13120
	ds_read_b32 v20, v187 offset:13376
	v_pk_fma_f32 v[144:145], v[30:31], v[92:93], v[96:97] op_sel_hi:[1,0,1]
	v_pk_fma_f32 v[146:147], v[32:33], v[92:93], v[98:99] op_sel_hi:[1,0,1]
	ds_write_b32 v189, v100 offset:1536
	v_pk_mul_f32 v[102:103], v[144:145], v[38:39]
	v_pk_fma_f32 v[102:103], v[146:147], v[40:41], v[102:103]
	s_waitcnt lgkmcnt(8)
	v_pk_mul_f32 v[92:93], v[144:145], v[48:49]
	v_pk_mul_f32 v[96:97], v[56:57], v[64:65] op_sel_hi:[1,0]
	v_pk_fma_f32 v[92:93], v[146:147], v[50:51], v[92:93]
	v_pk_mul_f32 v[98:99], v[58:59], v[64:65] op_sel_hi:[1,0]
	v_add_f32_e32 v102, v102, v103
	v_add_f32_e32 v92, v92, v93
	v_pk_fma_f32 v[96:97], v[144:145], v[44:45], v[96:97]
	v_pk_fma_f32 v[98:99], v[146:147], v[46:47], v[98:99]
	v_add_f32_dpp v92, v92, v92 row_ror:8 row_mask:0xf bank_mask:0xf bound_ctrl:1
	v_add_f32_dpp v102, v102, v102 row_ror:8 row_mask:0xf bank_mask:0xf bound_ctrl:1
	ds_read_b128 v[22:25], v186 offset:13440
	v_add_f32_dpp v92, v92, v92 row_ror:4 row_mask:0xf bank_mask:0xf bound_ctrl:1
	ds_read_b128 v[26:29], v186 offset:13696
	ds_read_b128 v[30:33], v186 offset:13952
	v_add_f32_dpp v92, v92, v92 row_ror:2 row_mask:0xf bank_mask:0xf bound_ctrl:1
	v_add_f32_dpp v102, v102, v102 row_ror:4 row_mask:0xf bank_mask:0xf bound_ctrl:1
	ds_read_b128 v[34:37], v186 offset:14208
	v_add_f32_dpp v92, v92, v92 row_ror:1 row_mask:0xf bank_mask:0xf bound_ctrl:1
	ds_read_b128 v[38:41], v186 offset:14464
	ds_read_b32 v42, v187 offset:14720
	v_pk_fma_f32 v[144:145], v[52:53], v[92:93], v[96:97] op_sel_hi:[1,0,1]
	v_pk_fma_f32 v[146:147], v[54:55], v[92:93], v[98:99] op_sel_hi:[1,0,1]
	ds_write_b32 v189, v102 offset:1792
	v_pk_mul_f32 v[100:101], v[144:145], v[60:61]
	v_pk_fma_f32 v[100:101], v[146:147], v[62:63], v[100:101]
	s_waitcnt lgkmcnt(8)
	v_pk_mul_f32 v[92:93], v[144:145], v[4:5]
	v_pk_mul_f32 v[96:97], v[12:13], v[20:21] op_sel_hi:[1,0]
	v_pk_fma_f32 v[92:93], v[146:147], v[6:7], v[92:93]
	v_pk_mul_f32 v[98:99], v[14:15], v[20:21] op_sel_hi:[1,0]
	v_add_f32_e32 v100, v100, v101
	v_add_f32_e32 v92, v92, v93
	v_pk_fma_f32 v[96:97], v[144:145], v[0:1], v[96:97]
	v_pk_fma_f32 v[98:99], v[146:147], v[2:3], v[98:99]
	v_add_f32_dpp v92, v92, v92 row_ror:8 row_mask:0xf bank_mask:0xf bound_ctrl:1
	v_add_f32_dpp v100, v100, v100 row_ror:8 row_mask:0xf bank_mask:0xf bound_ctrl:1
	ds_read_b128 v[44:47], v186 offset:14784
	v_add_f32_dpp v92, v92, v92 row_ror:4 row_mask:0xf bank_mask:0xf bound_ctrl:1
	ds_read_b128 v[48:51], v186 offset:15040
	ds_read_b128 v[52:55], v186 offset:15296
	v_add_f32_dpp v92, v92, v92 row_ror:2 row_mask:0xf bank_mask:0xf bound_ctrl:1
	v_add_f32_dpp v100, v100, v100 row_ror:4 row_mask:0xf bank_mask:0xf bound_ctrl:1
	ds_read_b128 v[56:59], v186 offset:15552
	v_add_f32_dpp v92, v92, v92 row_ror:1 row_mask:0xf bank_mask:0xf bound_ctrl:1
	ds_read_b128 v[60:63], v186 offset:15808
	ds_read_b32 v64, v187 offset:16064
	v_pk_fma_f32 v[144:145], v[8:9], v[92:93], v[96:97] op_sel_hi:[1,0,1]
	v_pk_fma_f32 v[146:147], v[10:11], v[92:93], v[98:99] op_sel_hi:[1,0,1]
	ds_write_b32 v189, v100 offset:2048
	v_pk_mul_f32 v[102:103], v[144:145], v[16:17]
	v_pk_fma_f32 v[102:103], v[146:147], v[18:19], v[102:103]
	s_waitcnt lgkmcnt(8)
	v_pk_mul_f32 v[92:93], v[144:145], v[26:27]
	v_pk_mul_f32 v[96:97], v[34:35], v[42:43] op_sel_hi:[1,0]
	v_pk_fma_f32 v[92:93], v[146:147], v[28:29], v[92:93]
	v_pk_mul_f32 v[98:99], v[36:37], v[42:43] op_sel_hi:[1,0]
	v_add_f32_e32 v102, v102, v103
	v_add_f32_e32 v92, v92, v93
	v_pk_fma_f32 v[96:97], v[144:145], v[22:23], v[96:97]
	v_pk_fma_f32 v[98:99], v[146:147], v[24:25], v[98:99]
	v_add_f32_dpp v92, v92, v92 row_ror:8 row_mask:0xf bank_mask:0xf bound_ctrl:1
	v_add_f32_dpp v102, v102, v102 row_ror:8 row_mask:0xf bank_mask:0xf bound_ctrl:1
	ds_read_b128 v[0:3], v186 offset:16128
	v_add_f32_dpp v92, v92, v92 row_ror:4 row_mask:0xf bank_mask:0xf bound_ctrl:1
	ds_read_b128 v[4:7], v186 offset:16384
	ds_read_b128 v[8:11], v186 offset:16640
	v_add_f32_dpp v92, v92, v92 row_ror:2 row_mask:0xf bank_mask:0xf bound_ctrl:1
	v_add_f32_dpp v102, v102, v102 row_ror:4 row_mask:0xf bank_mask:0xf bound_ctrl:1
	ds_read_b128 v[12:15], v186 offset:16896
	v_add_f32_dpp v92, v92, v92 row_ror:1 row_mask:0xf bank_mask:0xf bound_ctrl:1
	ds_read_b128 v[16:19], v186 offset:17152
	ds_read_b32 v20, v187 offset:17408
	v_pk_fma_f32 v[144:145], v[30:31], v[92:93], v[96:97] op_sel_hi:[1,0,1]
	v_pk_fma_f32 v[146:147], v[32:33], v[92:93], v[98:99] op_sel_hi:[1,0,1]
	ds_write_b32 v189, v102 offset:2304
	v_pk_mul_f32 v[100:101], v[144:145], v[38:39]
	v_pk_fma_f32 v[100:101], v[146:147], v[40:41], v[100:101]
	s_waitcnt lgkmcnt(8)
; template <int CTRL> __device__ __forceinline__ float dpp_add(float x) { const int y = __builtin_amdgcn_update_dpp(0, __float_as_int(x), CTRL, 0xf, 0xf, false); return x + __int_as_float(y); }
; __device__ __forceinline__ float row16_sum(float x) { x = dpp_add<0x128>(x); x = dpp_add<0x124>(x); x = dpp_add<0x122>(x); x = dpp_add<0x121>(x); return x; }
; #define LO2(x) __builtin_shufflevector(x, x, 0, 1)
; #define HI2(x) __builtin_shufflevector(x, x, 2, 3)
; template <int DIR> __device__ __forceinline__ void rwkv_scan_dir(const Params& P, unsigned char* lds, int sb, int tid) {
;     ...
;             for (int st = 0; st < SC_CH; ++st) {
;                 const float* rn = rp + (st + 2) * 336;
;                 const f32x4 nw = *(const f32x4*)(rn), nkk = *(const f32x4*)(rn + 64), nkka = *(const f32x4*)(rn + 128), nkm = *(const f32x4*)(rn + 192), nr = *(const f32x4*)(rn + 256);
;                 const float nv = vp[(st + 2) * 336];
;                 f32x2 q = sA * LO2(kk); q = sB * HI2(kk) + q;
;                 float sk = q.x + q.y;
;                 float yy = 0.f;
;                 if (DIR == 1) { f32x2 yq = sA * LO2(r); yq = sB * HI2(r) + yq; yy = yq.x + yq.y; }
;                 sk = row16_sum(sk);
;                 f32x2 tA = LO2(km) * v, tB = HI2(km) * v;
;                 tA = sA * LO2(w) + tA; tB = sB * HI2(w) + tB;
;                 sA = LO2(kka) * sk + tA; sB = HI2(kka) * sk + tB;
;                 if (DIR == 0) { f32x2 yq = sA * LO2(r); yq = sB * HI2(r) + yq; yy = yq.x + yq.y; }
;                 yy = dpp_add<0x128>(yy); yy = dpp_add<0x124>(yy);
;                 yp[st * 64] = yy;
;                 w = w1; kk = kk1; kka = kka1; km = km1; r = r1; v = v1;
;                 w1 = nw; kk1 = nkk; kka1 = nkka; km1 = nkm; r1 = nr; v1 = nv;
	v_pk_mul_f32 v[92:93], v[144:145], v[48:49]
	v_pk_mul_f32 v[96:97], v[56:57], v[64:65] op_sel_hi:[1,0]
	v_pk_fma_f32 v[92:93], v[146:147], v[50:51], v[92:93]
	v_pk_mul_f32 v[98:99], v[58:59], v[64:65] op_sel_hi:[1,0]
	v_add_f32_e32 v100, v100, v101
	v_add_f32_e32 v92, v92, v93
	v_pk_fma_f32 v[96:97], v[144:145], v[44:45], v[96:97]
	v_pk_fma_f32 v[98:99], v[146:147], v[46:47], v[98:99]
	v_add_f32_dpp v92, v92, v92 row_ror:8 row_mask:0xf bank_mask:0xf bound_ctrl:1
	v_add_f32_dpp v100, v100, v100 row_ror:8 row_mask:0xf bank_mask:0xf bound_ctrl:1
	ds_read_b128 v[22:25], v186 offset:17472
	v_add_f32_dpp v92, v92, v92 row_ror:4 row_mask:0xf bank_mask:0xf bound_ctrl:1
	ds_read_b128 v[26:29], v186 offset:17728
	ds_read_b128 v[30:33], v186 offset:17984
	v_add_f32_dpp v92, v92, v92 row_ror:2 row_mask:0xf bank_mask:0xf bound_ctrl:1
	v_add_f32_dpp v100, v100, v100 row_ror:4 row_mask:0xf bank_mask:0xf bound_ctrl:1
	ds_read_b128 v[34:37], v186 offset:18240
	v_add_f32_dpp v92, v92, v92 row_ror:1 row_mask:0xf bank_mask:0xf bound_ctrl:1
	ds_read_b128 v[38:41], v186 offset:18496
	ds_read_b32 v42, v187 offset:18752
	v_pk_fma_f32 v[144:145], v[52:53], v[92:93], v[96:97] op_sel_hi:[1,0,1]
	v_pk_fma_f32 v[146:147], v[54:55], v[92:93], v[98:99] op_sel_hi:[1,0,1]
	ds_write_b32 v189, v100 offset:2560
	v_pk_mul_f32 v[102:103], v[144:145], v[60:61]
	v_pk_fma_f32 v[102:103], v[146:147], v[62:63], v[102:103]
	s_waitcnt lgkmcnt(8)
	v_pk_mul_f32 v[92:93], v[144:145], v[4:5]
	v_pk_mul_f32 v[96:97], v[12:13], v[20:21] op_sel_hi:[1,0]
	v_pk_fma_f32 v[92:93], v[146:147], v[6:7], v[92:93]
	v_pk_mul_f32 v[98:99], v[14:15], v[20:21] op_sel_hi:[1,0]
	v_add_f32_e32 v102, v102, v103
	v_add_f32_e32 v92, v92, v93
	v_pk_fma_f32 v[96:97], v[144:145], v[0:1], v[96:97]
	v_pk_fma_f32 v[98:99], v[146:147], v[2:3], v[98:99]
	v_add_f32_dpp v92, v92, v92 row_ror:8 row_mask:0xf bank_mask:0xf bound_ctrl:1
	v_add_f32_dpp v102, v102, v102 row_ror:8 row_mask:0xf bank_mask:0xf bound_ctrl:1
	ds_read_b128 v[44:47], v186 offset:18816
	v_add_f32_dpp v92, v92, v92 row_ror:4 row_mask:0xf bank_mask:0xf bound_ctrl:1
	ds_read_b128 v[48:51], v186 offset:19072
	ds_read_b128 v[52:55], v186 offset:19328
	v_add_f32_dpp v92, v92, v92 row_ror:2 row_mask:0xf bank_mask:0xf bound_ctrl:1
	v_add_f32_dpp v102, v102, v102 row_ror:4 row_mask:0xf bank_mask:0xf bound_ctrl:1
	ds_read_b128 v[56:59], v186 offset:19584
	v_add_f32_dpp v92, v92, v92 row_ror:1 row_mask:0xf bank_mask:0xf bound_ctrl:1
	ds_read_b128 v[60:63], v186 offset:19840
	ds_read_b32 v64, v187 offset:20096
	v_pk_fma_f32 v[144:145], v[8:9], v[92:93], v[96:97] op_sel_hi:[1,0,1]
	v_pk_fma_f32 v[146:147], v[10:11], v[92:93], v[98:99] op_sel_hi:[1,0,1]
	ds_write_b32 v189, v102 offset:2816
	v_pk_mul_f32 v[100:101], v[144:145], v[16:17]
	v_pk_fma_f32 v[100:101], v[146:147], v[18:19], v[100:101]
	s_waitcnt lgkmcnt(8)
	v_pk_mul_f32 v[92:93], v[144:145], v[26:27]
	v_pk_mul_f32 v[96:97], v[34:35], v[42:43] op_sel_hi:[1,0]
	v_pk_fma_f32 v[92:93], v[146:147], v[28:29], v[92:93]
	v_pk_mul_f32 v[98:99], v[36:37], v[42:43] op_sel_hi:[1,0]
	v_add_f32_e32 v100, v100, v101
	v_add_f32_e32 v92, v92, v93
	v_pk_fma_f32 v[96:97], v[144:145], v[22:23], v[96:97]
	v_pk_fma_f32 v[98:99], v[146:147], v[24:25], v[98:99]
	v_add_f32_dpp v92, v92, v92 row_ror:8 row_mask:0xf bank_mask:0xf bound_ctrl:1
	v_add_f32_dpp v100, v100, v100 row_ror:8 row_mask:0xf bank_mask:0xf bound_ctrl:1
	ds_read_b128 v[0:3], v186 offset:20160
	v_add_f32_dpp v92, v92, v92 row_ror:4 row_mask:0xf bank_mask:0xf bound_ctrl:1
	ds_read_b128 v[4:7], v186 offset:20416
	ds_read_b128 v[8:11], v186 offset:20672
	v_add_f32_dpp v92, v92, v92 row_ror:2 row_mask:0xf bank_mask:0xf bound_ctrl:1
	v_add_f32_dpp v100, v100, v100 row_ror:4 row_mask:0xf bank_mask:0xf bound_ctrl:1
	ds_read_b128 v[12:15], v186 offset:20928
	v_add_f32_dpp v92, v92, v92 row_ror:1 row_mask:0xf bank_mask:0xf bound_ctrl:1
	ds_read_b128 v[16:19], v186 offset:21184
	ds_read_b32 v20, v187 offset:21440
	v_pk_fma_f32 v[144:145], v[30:31], v[92:93], v[96:97] op_sel_hi:[1,0,1]
	v_pk_fma_f32 v[146:147], v[32:33], v[92:93], v[98:99] op_sel_hi:[1,0,1]
	ds_write_b32 v189, v100 offset:3072
	v_pk_mul_f32 v[102:103], v[144:145], v[38:39]
	v_pk_fma_f32 v[102:103], v[146:147], v[40:41], v[102:103]
	s_waitcnt lgkmcnt(8)
	v_pk_mul_f32 v[92:93], v[144:145], v[48:49]
	v_pk_mul_f32 v[96:97], v[56:57], v[64:65] op_sel_hi:[1,0]
	v_pk_fma_f32 v[92:93], v[146:147], v[50:51], v[92:93]
	v_pk_mul_f32 v[98:99], v[58:59], v[64:65] op_sel_hi:[1,0]
	v_add_f32_e32 v102, v102, v103
	v_add_f32_e32 v92, v92, v93
	v_pk_fma_f32 v[96:97], v[144:145], v[44:45], v[96:97]
	v_pk_fma_f32 v[98:99], v[146:147], v[46:47], v[98:99]
	v_add_f32_dpp v92, v92, v92 row_ror:8 row_mask:0xf bank_mask:0xf bound_ctrl:1
	v_add_f32_dpp v102, v102, v102 row_ror:8 row_mask:0xf bank_mask:0xf bound_ctrl:1
	s_nop 0
	v_add_f32_dpp v92, v92, v92 row_ror:4 row_mask:0xf bank_mask:0xf bound_ctrl:1
	s_nop 0
	s_nop 0
	v_add_f32_dpp v92, v92, v92 row_ror:2 row_mask:0xf bank_mask:0xf bound_ctrl:1
	v_add_f32_dpp v102, v102, v102 row_ror:4 row_mask:0xf bank_mask:0xf bound_ctrl:1
	s_nop 0
	v_add_f32_dpp v92, v92, v92 row_ror:1 row_mask:0xf bank_mask:0xf bound_ctrl:1
	s_nop 0
	s_nop 0
	v_pk_fma_f32 v[144:145], v[52:53], v[92:93], v[96:97] op_sel_hi:[1,0,1]
	v_pk_fma_f32 v[146:147], v[54:55], v[92:93], v[98:99] op_sel_hi:[1,0,1]
	ds_write_b32 v189, v102 offset:3328
	v_pk_mul_f32 v[100:101], v[144:145], v[60:61]
	v_pk_fma_f32 v[100:101], v[146:147], v[62:63], v[100:101]
	s_waitcnt lgkmcnt(2)
	v_pk_mul_f32 v[92:93], v[144:145], v[4:5]
	v_pk_mul_f32 v[96:97], v[12:13], v[20:21] op_sel_hi:[1,0]
	v_pk_fma_f32 v[92:93], v[146:147], v[6:7], v[92:93]
	v_pk_mul_f32 v[98:99], v[14:15], v[20:21] op_sel_hi:[1,0]
	v_add_f32_e32 v100, v100, v101
	v_add_f32_e32 v92, v92, v93
	v_pk_fma_f32 v[96:97], v[144:145], v[0:1], v[96:97]
	v_pk_fma_f32 v[98:99], v[146:147], v[2:3], v[98:99]
	v_add_f32_dpp v92, v92, v92 row_ror:8 row_mask:0xf bank_mask:0xf bound_ctrl:1
	v_add_f32_dpp v100, v100, v100 row_ror:8 row_mask:0xf bank_mask:0xf bound_ctrl:1
	s_nop 0
	v_add_f32_dpp v92, v92, v92 row_ror:4 row_mask:0xf bank_mask:0xf bound_ctrl:1
	s_nop 0
	s_nop 0
	v_add_f32_dpp v92, v92, v92 row_ror:2 row_mask:0xf bank_mask:0xf bound_ctrl:1
	v_add_f32_dpp v100, v100, v100 row_ror:4 row_mask:0xf bank_mask:0xf bound_ctrl:1
	s_nop 0
	v_add_f32_dpp v92, v92, v92 row_ror:1 row_mask:0xf bank_mask:0xf bound_ctrl:1
	s_nop 0
	s_nop 0
	v_pk_fma_f32 v[144:145], v[8:9], v[92:93], v[96:97] op_sel_hi:[1,0,1]
	v_pk_fma_f32 v[146:147], v[10:11], v[92:93], v[98:99] op_sel_hi:[1,0,1]
	ds_write_b32 v189, v100 offset:3584
	v_pk_mul_f32 v[102:103], v[144:145], v[16:17]
	v_pk_fma_f32 v[102:103], v[146:147], v[18:19], v[102:103]
	v_add_f32_e32 v102, v102, v103
	s_nop 1
	v_add_f32_dpp v102, v102, v102 row_ror:8 row_mask:0xf bank_mask:0xf bound_ctrl:1
	s_nop 1
	v_add_f32_dpp v102, v102, v102 row_ror:4 row_mask:0xf bank_mask:0xf bound_ctrl:1
	ds_write_b32 v189, v102 offset:3840
	v_add_u32_e32 v85, 1, v185

; #define LAUNDER_V(x) asm volatile("" : "+v"(x))
; template <int CTRL> __device__ __forceinline__ float dpp_add(float x) { const int y = __builtin_amdgcn_update_dpp(0, __float_as_int(x), CTRL, 0xf, 0xf, false); return x + __int_as_float(y); }
; #define LO2(x) __builtin_shufflevector(x, x, 0, 1)
; #define HI2(x) __builtin_shufflevector(x, x, 2, 3)
; template <int DIR> __device__ __forceinline__ void rwkv_scan_dir(const Params& P, unsigned char* lds, int sb, int tid) {
;     ...
;             const float* rp = buf + (ck % SC_NB) * SC_BUF + 4 * j;
;             const float* vp = buf + (ck % SC_NB) * SC_BUF + 320 + rowi;
;             int yoff = (ck & 1) * SC_YP + rowi * 4 + (j & 3); LAUNDER_V(yoff);
;             float* yp = ypart + yoff;
;             f32x4 w = *(const f32x4*)(rp), kk = *(const f32x4*)(rp + 64), kka = *(const f32x4*)(rp + 128), km = *(const f32x4*)(rp + 192), r = *(const f32x4*)(rp + 256);
;             float v = *vp;
;             f32x4 w1 = *(const f32x4*)(rp + 336), kk1 = *(const f32x4*)(rp + 336 + 64), kka1 = *(const f32x4*)(rp + 336 + 128), km1 = *(const f32x4*)(rp + 336 + 192), r1 = *(const f32x4*)(rp + 336 + 256);
;             float v1 = vp[336];
;     ...
; #pragma unroll 8
;             for (int st = 0; st < SC_CH; ++st) {
;                 const float* rn = rp + (st + 2) * 336;
;                 const f32x4 nw = *(const f32x4*)(rn), nkk = *(const f32x4*)(rn + 64), nkka = *(const f32x4*)(rn + 128), nkm = *(const f32x4*)(rn + 192), nr = *(const f32x4*)(rn + 256);
;                 const float nv = vp[(st + 2) * 336];
;                 f32x2 q = sA * LO2(kk); q = sB * HI2(kk) + q;
;                 float sk = q.x + q.y;
;                 float yy = 0.f;
;                 if (DIR == 1) { f32x2 yq = sA * LO2(r); yq = sB * HI2(r) + yq; yy = yq.x + yq.y; }
;                 sk = row16_sum(sk);
;                 f32x2 tA = LO2(km) * v, tB = HI2(km) * v;
;                 tA = sA * LO2(w) + tA; tB = sB * HI2(w) + tB;
;                 sA = LO2(kka) * sk + tA; sB = HI2(kka) * sk + tB;
;                 if (DIR == 0) { f32x2 yq = sA * LO2(r); yq = sB * HI2(r) + yq; yy = yq.x + yq.y; }
;                 yy = dpp_add<0x128>(yy); yy = dpp_add<0x124>(yy);
;                 yp[st * 64] = yy;
;                 w = w1; kk = kk1; kka = kka1; km = km1; r = r1; v = v1;
;                 w1 = nw; kk1 = nkk; kka1 = nkka; km1 = nkm; r1 = nr; v1 = nv;
.LBB0_97:
	s_and_saveexec_b64 s[6:7], s[4:5]
	s_xor_b64 s[6:7], exec, s[6:7]
	s_cbranch_execz .LBB0_101
	s_waitcnt lgkmcnt(0)
	v_mul_u32_u24_e32 v118, 0xcd, v162
	v_lshrrev_b32_e32 v118, 10, v118
	v_mul_u32_u24_e32 v119, 5, v118
	v_sub_u32_e32 v118, v162, v119
	v_mul_u32_u24_e32 v119, 0x5400, v118
	v_lshl_add_u32 v186, v156, 2, v119
	v_lshl_add_u32 v187, v164, 2, v119
	ds_read_b128 v[0:3], v186 offset:0
	ds_read_b128 v[4:7], v186 offset:256
	ds_read_b128 v[8:11], v186 offset:512
	ds_read_b128 v[12:15], v186 offset:768
	ds_read_b128 v[16:19], v186 offset:1024
	ds_read_b32 v20, v187 offset:1280
	ds_read_b128 v[22:25], v186 offset:1344
	ds_read_b128 v[26:29], v186 offset:1600
	ds_read_b128 v[30:33], v186 offset:1856
	ds_read_b128 v[34:37], v186 offset:2112
	ds_read_b128 v[38:41], v186 offset:2368
	ds_read_b32 v42, v187 offset:2624
	v_lshlrev_b32_e32 v189, 10, v162
	v_and_b32_e32 v189, 0x400, v189
	v_or_b32_e32 v189, v189, v125
	v_lshlrev_b32_e32 v189, 2, v189
	v_add_u32_e32 v189, 0x1b400, v189
	s_waitcnt lgkmcnt(6)
	v_pk_mul_f32 v[92:93], v[144:145], v[4:5]
	v_pk_mul_f32 v[100:101], v[144:145], v[16:17]
	v_pk_fma_f32 v[92:93], v[146:147], v[6:7], v[92:93]
	v_pk_fma_f32 v[100:101], v[146:147], v[18:19], v[100:101]
	v_pk_mul_f32 v[96:97], v[12:13], v[20:21] op_sel_hi:[1,0]
	v_pk_mul_f32 v[98:99], v[14:15], v[20:21] op_sel_hi:[1,0]
	v_add_f32_e32 v92, v92, v93
	v_add_f32_e32 v100, v100, v101
	v_pk_fma_f32 v[96:97], v[144:145], v[0:1], v[96:97]
	v_pk_fma_f32 v[98:99], v[146:147], v[2:3], v[98:99]
	v_add_f32_dpp v92, v92, v92 row_ror:8 row_mask:0xf bank_mask:0xf bound_ctrl:1
	v_add_f32_dpp v100, v100, v100 row_ror:8 row_mask:0xf bank_mask:0xf bound_ctrl:1
	ds_read_b128 v[44:47], v186 offset:2688
	v_add_f32_dpp v92, v92, v92 row_ror:4 row_mask:0xf bank_mask:0xf bound_ctrl:1
	ds_read_b128 v[48:51], v186 offset:2944
	ds_read_b128 v[52:55], v186 offset:3200
	v_add_f32_dpp v92, v92, v92 row_ror:2 row_mask:0xf bank_mask:0xf bound_ctrl:1
	v_add_f32_dpp v100, v100, v100 row_ror:4 row_mask:0xf bank_mask:0xf bound_ctrl:1
	ds_read_b128 v[56:59], v186 offset:3456
	v_add_f32_dpp v92, v92, v92 row_ror:1 row_mask:0xf bank_mask:0xf bound_ctrl:1
	ds_read_b128 v[60:63], v186 offset:3712
	ds_read_b32 v64, v187 offset:3968
	v_pk_fma_f32 v[144:145], v[8:9], v[92:93], v[96:97] op_sel_hi:[1,0,1]
	v_pk_fma_f32 v[146:147], v[10:11], v[92:93], v[98:99] op_sel_hi:[1,0,1]
	ds_write_b32 v189, v100 offset:0
	s_waitcnt lgkmcnt(7)
	v_pk_mul_f32 v[92:93], v[144:145], v[26:27]
	v_pk_mul_f32 v[102:103], v[144:145], v[38:39]
	v_pk_fma_f32 v[92:93], v[146:147], v[28:29], v[92:93]
	v_pk_fma_f32 v[102:103], v[146:147], v[40:41], v[102:103]
	v_pk_mul_f32 v[96:97], v[34:35], v[42:43] op_sel_hi:[1,0]
	v_pk_mul_f32 v[98:99], v[36:37], v[42:43] op_sel_hi:[1,0]
	v_add_f32_e32 v92, v92, v93
	v_add_f32_e32 v102, v102, v103
	v_pk_fma_f32 v[96:97], v[144:145], v[22:23], v[96:97]
	v_pk_fma_f32 v[98:99], v[146:147], v[24:25], v[98:99]
	v_add_f32_dpp v92, v92, v92 row_ror:8 row_mask:0xf bank_mask:0xf bound_ctrl:1
	v_add_f32_dpp v102, v102, v102 row_ror:8 row_mask:0xf bank_mask:0xf bound_ctrl:1
	ds_read_b128 v[0:3], v186 offset:4032
	v_add_f32_dpp v92, v92, v92 row_ror:4 row_mask:0xf bank_mask:0xf bound_ctrl:1
	ds_read_b128 v[4:7], v186 offset:4288
	ds_read_b128 v[8:11], v186 offset:4544
	v_add_f32_dpp v92, v92, v92 row_ror:2 row_mask:0xf bank_mask:0xf bound_ctrl:1
	v_add_f32_dpp v102, v102, v102 row_ror:4 row_mask:0xf bank_mask:0xf bound_ctrl:1
	ds_read_b128 v[12:15], v186 offset:4800
	v_add_f32_dpp v92, v92, v92 row_ror:1 row_mask:0xf bank_mask:0xf bound_ctrl:1
	ds_read_b128 v[16:19], v186 offset:5056
	ds_read_b32 v20, v187 offset:5312
	v_pk_fma_f32 v[144:145], v[30:31], v[92:93], v[96:97] op_sel_hi:[1,0,1]
	v_pk_fma_f32 v[146:147], v[32:33], v[92:93], v[98:99] op_sel_hi:[1,0,1]
	ds_write_b32 v189, v102 offset:256
	s_waitcnt lgkmcnt(8)
	v_pk_mul_f32 v[92:93], v[144:145], v[48:49]
	v_pk_mul_f32 v[100:101], v[144:145], v[60:61]
	v_pk_fma_f32 v[92:93], v[146:147], v[50:51], v[92:93]
	v_pk_fma_f32 v[100:101], v[146:147], v[62:63], v[100:101]
	v_pk_mul_f32 v[96:97], v[56:57], v[64:65] op_sel_hi:[1,0]
	v_pk_mul_f32 v[98:99], v[58:59], v[64:65] op_sel_hi:[1,0]
	v_add_f32_e32 v92, v92, v93
	v_add_f32_e32 v100, v100, v101
	v_pk_fma_f32 v[96:97], v[144:145], v[44:45], v[96:97]
	v_pk_fma_f32 v[98:99], v[146:147], v[46:47], v[98:99]
	v_add_f32_dpp v92, v92, v92 row_ror:8 row_mask:0xf bank_mask:0xf bound_ctrl:1
	v_add_f32_dpp v100, v100, v100 row_ror:8 row_mask:0xf bank_mask:0xf bound_ctrl:1
	ds_read_b128 v[22:25], v186 offset:5376
	v_add_f32_dpp v92, v92, v92 row_ror:4 row_mask:0xf bank_mask:0xf bound_ctrl:1
	ds_read_b128 v[26:29], v186 offset:5632
	ds_read_b128 v[30:33], v186 offset:5888
	v_add_f32_dpp v92, v92, v92 row_ror:2 row_mask:0xf bank_mask:0xf bound_ctrl:1
	v_add_f32_dpp v100, v100, v100 row_ror:4 row_mask:0xf bank_mask:0xf bound_ctrl:1
	ds_read_b128 v[34:37], v186 offset:6144
	v_add_f32_dpp v92, v92, v92 row_ror:1 row_mask:0xf bank_mask:0xf bound_ctrl:1
	ds_read_b128 v[38:41], v186 offset:6400
	ds_read_b32 v42, v187 offset:6656
	v_pk_fma_f32 v[144:145], v[52:53], v[92:93], v[96:97] op_sel_hi:[1,0,1]
	v_pk_fma_f32 v[146:147], v[54:55], v[92:93], v[98:99] op_sel_hi:[1,0,1]
	ds_write_b32 v189, v100 offset:512
	s_waitcnt lgkmcnt(8)
; template <int CTRL> __device__ __forceinline__ float dpp_add(float x) { const int y = __builtin_amdgcn_update_dpp(0, __float_as_int(x), CTRL, 0xf, 0xf, false); return x + __int_as_float(y); }
; __device__ __forceinline__ float row16_sum(float x) { x = dpp_add<0x128>(x); x = dpp_add<0x124>(x); x = dpp_add<0x122>(x); x = dpp_add<0x121>(x); return x; }
; #define LO2(x) __builtin_shufflevector(x, x, 0, 1)
; #define HI2(x) __builtin_shufflevector(x, x, 2, 3)
; template <int DIR> __device__ __forceinline__ void rwkv_scan_dir(const Params& P, unsigned char* lds, int sb, int tid) {
;     ...
;             for (int st = 0; st < SC_CH; ++st) {
;                 const float* rn = rp + (st + 2) * 336;
;                 const f32x4 nw = *(const f32x4*)(rn), nkk = *(const f32x4*)(rn + 64), nkka = *(const f32x4*)(rn + 128), nkm = *(const f32x4*)(rn + 192), nr = *(const f32x4*)(rn + 256);
;                 const float nv = vp[(st + 2) * 336];
;                 f32x2 q = sA * LO2(kk); q = sB * HI2(kk) + q;
;                 float sk = q.x + q.y;
;                 float yy = 0.f;
;                 if (DIR == 1) { f32x2 yq = sA * LO2(r); yq = sB * HI2(r) + yq; yy = yq.x + yq.y; }
;                 sk = row16_sum(sk);
;                 f32x2 tA = LO2(km) * v, tB = HI2(km) * v;
;                 tA = sA * LO2(w) + tA; tB = sB * HI2(w) + tB;
;                 sA = LO2(kka) * sk + tA; sB = HI2(kka) * sk + tB;
;                 if (DIR == 0) { f32x2 yq = sA * LO2(r); yq = sB * HI2(r) + yq; yy = yq.x + yq.y; }
;                 yy = dpp_add<0x128>(yy); yy = dpp_add<0x124>(yy);
;                 yp[st * 64] = yy;
;                 w = w1; kk = kk1; kka = kka1; km = km1; r = r1; v = v1;
;                 w1 = nw; kk1 = nkk; kka1 = nkka; km1 = nkm; r1 = nr; v1 = nv;
	v_pk_mul_f32 v[92:93], v[144:145], v[4:5]
	v_pk_mul_f32 v[102:103], v[144:145], v[16:17]
	v_pk_fma_f32 v[92:93], v[146:147], v[6:7], v[92:93]
	v_pk_fma_f32 v[102:103], v[146:147], v[18:19], v[102:103]
	v_pk_mul_f32 v[96:97], v[12:13], v[20:21] op_sel_hi:[1,0]
	v_pk_mul_f32 v[98:99], v[14:15], v[20:21] op_sel_hi:[1,0]
	v_add_f32_e32 v92, v92, v93
	v_add_f32_e32 v102, v102, v103
	v_pk_fma_f32 v[96:97], v[144:145], v[0:1], v[96:97]
	v_pk_fma_f32 v[98:99], v[146:147], v[2:3], v[98:99]
	v_add_f32_dpp v92, v92, v92 row_ror:8 row_mask:0xf bank_mask:0xf bound_ctrl:1
	v_add_f32_dpp v102, v102, v102 row_ror:8 row_mask:0xf bank_mask:0xf bound_ctrl:1
	ds_read_b128 v[44:47], v186 offset:6720
	v_add_f32_dpp v92, v92, v92 row_ror:4 row_mask:0xf bank_mask:0xf bound_ctrl:1
	ds_read_b128 v[48:51], v186 offset:6976
	ds_read_b128 v[52:55], v186 offset:7232
	v_add_f32_dpp v92, v92, v92 row_ror:2 row_mask:0xf bank_mask:0xf bound_ctrl:1
	v_add_f32_dpp v102, v102, v102 row_ror:4 row_mask:0xf bank_mask:0xf bound_ctrl:1
	ds_read_b128 v[56:59], v186 offset:7488
	v_add_f32_dpp v92, v92, v92 row_ror:1 row_mask:0xf bank_mask:0xf bound_ctrl:1
	ds_read_b128 v[60:63], v186 offset:7744
	ds_read_b32 v64, v187 offset:8000
	v_pk_fma_f32 v[144:145], v[8:9], v[92:93], v[96:97] op_sel_hi:[1,0,1]
	v_pk_fma_f32 v[146:147], v[10:11], v[92:93], v[98:99] op_sel_hi:[1,0,1]
	ds_write_b32 v189, v102 offset:768
	s_waitcnt lgkmcnt(8)
	v_pk_mul_f32 v[92:93], v[144:145], v[26:27]
	v_pk_mul_f32 v[100:101], v[144:145], v[38:39]
	v_pk_fma_f32 v[92:93], v[146:147], v[28:29], v[92:93]
	v_pk_fma_f32 v[100:101], v[146:147], v[40:41], v[100:101]
	v_pk_mul_f32 v[96:97], v[34:35], v[42:43] op_sel_hi:[1,0]
	v_pk_mul_f32 v[98:99], v[36:37], v[42:43] op_sel_hi:[1,0]
	v_add_f32_e32 v92, v92, v93
	v_add_f32_e32 v100, v100, v101
	v_pk_fma_f32 v[96:97], v[144:145], v[22:23], v[96:97]
	v_pk_fma_f32 v[98:99], v[146:147], v[24:25], v[98:99]
	v_add_f32_dpp v92, v92, v92 row_ror:8 row_mask:0xf bank_mask:0xf bound_ctrl:1
	v_add_f32_dpp v100, v100, v100 row_ror:8 row_mask:0xf bank_mask:0xf bound_ctrl:1
	ds_read_b128 v[0:3], v186 offset:8064
	v_add_f32_dpp v92, v92, v92 row_ror:4 row_mask:0xf bank_mask:0xf bound_ctrl:1
	ds_read_b128 v[4:7], v186 offset:8320
	ds_read_b128 v[8:11], v186 offset:8576
	v_add_f32_dpp v92, v92, v92 row_ror:2 row_mask:0xf bank_mask:0xf bound_ctrl:1
	v_add_f32_dpp v100, v100, v100 row_ror:4 row_mask:0xf bank_mask:0xf bound_ctrl:1
	ds_read_b128 v[12:15], v186 offset:8832
	v_add_f32_dpp v92, v92, v92 row_ror:1 row_mask:0xf bank_mask:0xf bound_ctrl:1
	ds_read_b128 v[16:19], v186 offset:9088
	ds_read_b32 v20, v187 offset:9344
	v_pk_fma_f32 v[144:145], v[30:31], v[92:93], v[96:97] op_sel_hi:[1,0,1]
	v_pk_fma_f32 v[146:147], v[32:33], v[92:93], v[98:99] op_sel_hi:[1,0,1]
	ds_write_b32 v189, v100 offset:1024
	s_waitcnt lgkmcnt(8)
	v_pk_mul_f32 v[92:93], v[144:145], v[48:49]
	v_pk_mul_f32 v[102:103], v[144:145], v[60:61]
	v_pk_fma_f32 v[92:93], v[146:147], v[50:51], v[92:93]
	v_pk_fma_f32 v[102:103], v[146:147], v[62:63], v[102:103]
	v_pk_mul_f32 v[96:97], v[56:57], v[64:65] op_sel_hi:[1,0]
	v_pk_mul_f32 v[98:99], v[58:59], v[64:65] op_sel_hi:[1,0]
	v_add_f32_e32 v92, v92, v93
	v_add_f32_e32 v102, v102, v103
	v_pk_fma_f32 v[96:97], v[144:145], v[44:45], v[96:97]
	v_pk_fma_f32 v[98:99], v[146:147], v[46:47], v[98:99]
	v_add_f32_dpp v92, v92, v92 row_ror:8 row_mask:0xf bank_mask:0xf bound_ctrl:1
	v_add_f32_dpp v102, v102, v102 row_ror:8 row_mask:0xf bank_mask:0xf bound_ctrl:1
	ds_read_b128 v[22:25], v186 offset:9408
	v_add_f32_dpp v92, v92, v92 row_ror:4 row_mask:0xf bank_mask:0xf bound_ctrl:1
	ds_read_b128 v[26:29], v186 offset:9664
	ds_read_b128 v[30:33], v186 offset:9920
	v_add_f32_dpp v92, v92, v92 row_ror:2 row_mask:0xf bank_mask:0xf bound_ctrl:1
	v_add_f32_dpp v102, v102, v102 row_ror:4 row_mask:0xf bank_mask:0xf bound_ctrl:1
	ds_read_b128 v[34:37], v186 offset:10176
	v_add_f32_dpp v92, v92, v92 row_ror:1 row_mask:0xf bank_mask:0xf bound_ctrl:1
	ds_read_b128 v[38:41], v186 offset:10432
	ds_read_b32 v42, v187 offset:10688
	v_pk_fma_f32 v[144:145], v[52:53], v[92:93], v[96:97] op_sel_hi:[1,0,1]
	v_pk_fma_f32 v[146:147], v[54:55], v[92:93], v[98:99] op_sel_hi:[1,0,1]
	ds_write_b32 v189, v102 offset:1280
	s_waitcnt lgkmcnt(8)
	v_pk_mul_f32 v[92:93], v[144:145], v[4:5]
	v_pk_mul_f32 v[100:101], v[144:145], v[16:17]
	v_pk_fma_f32 v[92:93], v[146:147], v[6:7], v[92:93]
	v_pk_fma_f32 v[100:101], v[146:147], v[18:19], v[100:101]
	v_pk_mul_f32 v[96:97], v[12:13], v[20:21] op_sel_hi:[1,0]
	v_pk_mul_f32 v[98:99], v[14:15], v[20:21] op_sel_hi:[1,0]
	v_add_f32_e32 v92, v92, v93
	v_add_f32_e32 v100, v100, v101
	v_pk_fma_f32 v[96:97], v[144:145], v[0:1], v[96:97]
	v_pk_fma_f32 v[98:99], v[146:147], v[2:3], v[98:99]
	v_add_f32_dpp v92, v92, v92 row_ror:8 row_mask:0xf bank_mask:0xf bound_ctrl:1
	v_add_f32_dpp v100, v100, v100 row_ror:8 row_mask:0xf bank_mask:0xf bound_ctrl:1
	ds_read_b128 v[44:47], v186 offset:10752
	v_add_f32_dpp v92, v92, v92 row_ror:4 row_mask:0xf bank_mask:0xf bound_ctrl:1
	ds_read_b128 v[48:51], v186 offset:11008
	ds_read_b128 v[52:55], v186 offset:11264
	v_add_f32_dpp v92, v92, v92 row_ror:2 row_mask:0xf bank_mask:0xf bound_ctrl:1
	v_add_f32_dpp v100, v100, v100 row_ror:4 row_mask:0xf bank_mask:0xf bound_ctrl:1
	ds_read_b128 v[56:59], v186 offset:11520
	v_add_f32_dpp v92, v92, v92 row_ror:1 row_mask:0xf bank_mask:0xf bound_ctrl:1
	ds_read_b128 v[60:63], v186 offset:11776
	ds_read_b32 v64, v187 offset:12032
	v_pk_fma_f32 v[144:145], v[8:9], v[92:93], v[96:97] op_sel_hi:[1,0,1]
	v_pk_fma_f32 v[146:147], v[10:11], v[92:93], v[98:99] op_sel_hi:[1,0,1]
	ds_write_b32 v189, v100 offset:1536
	s_waitcnt lgkmcnt(8)
; template <int CTRL> __device__ __forceinline__ float dpp_add(float x) { const int y = __builtin_amdgcn_update_dpp(0, __float_as_int(x), CTRL, 0xf, 0xf, false); return x + __int_as_float(y); }
; __device__ __forceinline__ float row16_sum(float x) { x = dpp_add<0x128>(x); x = dpp_add<0x124>(x); x = dpp_add<0x122>(x); x = dpp_add<0x121>(x); return x; }
; #define LO2(x) __builtin_shufflevector(x, x, 0, 1)
; #define HI2(x) __builtin_shufflevector(x, x, 2, 3)
; template <int DIR> __device__ __forceinline__ void rwkv_scan_dir(const Params& P, unsigned char* lds, int sb, int tid) {
;     ...
;             for (int st = 0; st < SC_CH; ++st) {
;                 const float* rn = rp + (st + 2) * 336;
;                 const f32x4 nw = *(const f32x4*)(rn), nkk = *(const f32x4*)(rn + 64), nkka = *(const f32x4*)(rn + 128), nkm = *(const f32x4*)(rn + 192), nr = *(const f32x4*)(rn + 256);
;                 const float nv = vp[(st + 2) * 336];
;                 f32x2 q = sA * LO2(kk); q = sB * HI2(kk) + q;
;                 float sk = q.x + q.y;
;                 float yy = 0.f;
;                 if (DIR == 1) { f32x2 yq = sA * LO2(r); yq = sB * HI2(r) + yq; yy = yq.x + yq.y; }
;                 sk = row16_sum(sk);
;                 f32x2 tA = LO2(km) * v, tB = HI2(km) * v;
;                 tA = sA * LO2(w) + tA; tB = sB * HI2(w) + tB;
;                 sA = LO2(kka) * sk + tA; sB = HI2(kka) * sk + tB;
;                 if (DIR == 0) { f32x2 yq = sA * LO2(r); yq = sB * HI2(r) + yq; yy = yq.x + yq.y; }
;                 yy = dpp_add<0x128>(yy); yy = dpp_add<0x124>(yy);
;                 yp[st * 64] = yy;
;                 w = w1; kk = kk1; kka = kka1; km = km1; r = r1; v = v1;
;                 w1 = nw; kk1 = nkk; kka1 = nkka; km1 = nkm; r1 = nr; v1 = nv;
	v_pk_mul_f32 v[92:93], v[144:145], v[26:27]
	v_pk_mul_f32 v[102:103], v[144:145], v[38:39]
	v_pk_fma_f32 v[92:93], v[146:147], v[28:29], v[92:93]
	v_pk_fma_f32 v[102:103], v[146:147], v[40:41], v[102:103]
	v_pk_mul_f32 v[96:97], v[34:35], v[42:43] op_sel_hi:[1,0]
	v_pk_mul_f32 v[98:99], v[36:37], v[42:43] op_sel_hi:[1,0]
	v_add_f32_e32 v92, v92, v93
	v_add_f32_e32 v102, v102, v103
	v_pk_fma_f32 v[96:97], v[144:145], v[22:23], v[96:97]
	v_pk_fma_f32 v[98:99], v[146:147], v[24:25], v[98:99]
	v_add_f32_dpp v92, v92, v92 row_ror:8 row_mask:0xf bank_mask:0xf bound_ctrl:1
	v_add_f32_dpp v102, v102, v102 row_ror:8 row_mask:0xf bank_mask:0xf bound_ctrl:1
	ds_read_b128 v[0:3], v186 offset:12096
	v_add_f32_dpp v92, v92, v92 row_ror:4 row_mask:0xf bank_mask:0xf bound_ctrl:1
	ds_read_b128 v[4:7], v186 offset:12352
	ds_read_b128 v[8:11], v186 offset:12608
	v_add_f32_dpp v92, v92, v92 row_ror:2 row_mask:0xf bank_mask:0xf bound_ctrl:1
	v_add_f32_dpp v102, v102, v102 row_ror:4 row_mask:0xf bank_mask:0xf bound_ctrl:1
	ds_read_b128 v[12:15], v186 offset:12864
	v_add_f32_dpp v92, v92, v92 row_ror:1 row_mask:0xf bank_mask:0xf bound_ctrl:1
	ds_read_b128 v[16:19], v186 offset:13120
	ds_read_b32 v20, v187 offset:13376
	v_pk_fma_f32 v[144:145], v[30:31], v[92:93], v[96:97] op_sel_hi:[1,0,1]
	v_pk_fma_f32 v[146:147], v[32:33], v[92:93], v[98:99] op_sel_hi:[1,0,1]
	ds_write_b32 v189, v102 offset:1792
	s_waitcnt lgkmcnt(8)
	v_pk_mul_f32 v[92:93], v[144:145], v[48:49]
	v_pk_mul_f32 v[100:101], v[144:145], v[60:61]
	v_pk_fma_f32 v[92:93], v[146:147], v[50:51], v[92:93]
	v_pk_fma_f32 v[100:101], v[146:147], v[62:63], v[100:101]
	v_pk_mul_f32 v[96:97], v[56:57], v[64:65] op_sel_hi:[1,0]
	v_pk_mul_f32 v[98:99], v[58:59], v[64:65] op_sel_hi:[1,0]
	v_add_f32_e32 v92, v92, v93
	v_add_f32_e32 v100, v100, v101
	v_pk_fma_f32 v[96:97], v[144:145], v[44:45], v[96:97]
	v_pk_fma_f32 v[98:99], v[146:147], v[46:47], v[98:99]
	v_add_f32_dpp v92, v92, v92 row_ror:8 row_mask:0xf bank_mask:0xf bound_ctrl:1
	v_add_f32_dpp v100, v100, v100 row_ror:8 row_mask:0xf bank_mask:0xf bound_ctrl:1
	ds_read_b128 v[22:25], v186 offset:13440
	v_add_f32_dpp v92, v92, v92 row_ror:4 row_mask:0xf bank_mask:0xf bound_ctrl:1
	ds_read_b128 v[26:29], v186 offset:13696
	ds_read_b128 v[30:33], v186 offset:13952
	v_add_f32_dpp v92, v92, v92 row_ror:2 row_mask:0xf bank_mask:0xf bound_ctrl:1
	v_add_f32_dpp v100, v100, v100 row_ror:4 row_mask:0xf bank_mask:0xf bound_ctrl:1
	ds_read_b128 v[34:37], v186 offset:14208
	v_add_f32_dpp v92, v92, v92 row_ror:1 row_mask:0xf bank_mask:0xf bound_ctrl:1
	ds_read_b128 v[38:41], v186 offset:14464
	ds_read_b32 v42, v187 offset:14720
	v_pk_fma_f32 v[144:145], v[52:53], v[92:93], v[96:97] op_sel_hi:[1,0,1]
	v_pk_fma_f32 v[146:147], v[54:55], v[92:93], v[98:99] op_sel_hi:[1,0,1]
	ds_write_b32 v189, v100 offset:2048
	s_waitcnt lgkmcnt(8)
	v_pk_mul_f32 v[92:93], v[144:145], v[4:5]
	v_pk_mul_f32 v[102:103], v[144:145], v[16:17]
	v_pk_fma_f32 v[92:93], v[146:147], v[6:7], v[92:93]
	v_pk_fma_f32 v[102:103], v[146:147], v[18:19], v[102:103]
	v_pk_mul_f32 v[96:97], v[12:13], v[20:21] op_sel_hi:[1,0]
	v_pk_mul_f32 v[98:99], v[14:15], v[20:21] op_sel_hi:[1,0]
	v_add_f32_e32 v92, v92, v93
	v_add_f32_e32 v102, v102, v103
	v_pk_fma_f32 v[96:97], v[144:145], v[0:1], v[96:97]
	v_pk_fma_f32 v[98:99], v[146:147], v[2:3], v[98:99]
	v_add_f32_dpp v92, v92, v92 row_ror:8 row_mask:0xf bank_mask:0xf bound_ctrl:1
	v_add_f32_dpp v102, v102, v102 row_ror:8 row_mask:0xf bank_mask:0xf bound_ctrl:1
	ds_read_b128 v[44:47], v186 offset:14784
	v_add_f32_dpp v92, v92, v92 row_ror:4 row_mask:0xf bank_mask:0xf bound_ctrl:1
	ds_read_b128 v[48:51], v186 offset:15040
	ds_read_b128 v[52:55], v186 offset:15296
	v_add_f32_dpp v92, v92, v92 row_ror:2 row_mask:0xf bank_mask:0xf bound_ctrl:1
	v_add_f32_dpp v102, v102, v102 row_ror:4 row_mask:0xf bank_mask:0xf bound_ctrl:1
	ds_read_b128 v[56:59], v186 offset:15552
	v_add_f32_dpp v92, v92, v92 row_ror:1 row_mask:0xf bank_mask:0xf bound_ctrl:1
	ds_read_b128 v[60:63], v186 offset:15808
	ds_read_b32 v64, v187 offset:16064
	v_pk_fma_f32 v[144:145], v[8:9], v[92:93], v[96:97] op_sel_hi:[1,0,1]
	v_pk_fma_f32 v[146:147], v[10:11], v[92:93], v[98:99] op_sel_hi:[1,0,1]
	ds_write_b32 v189, v102 offset:2304
	s_waitcnt lgkmcnt(8)
	v_pk_mul_f32 v[92:93], v[144:145], v[26:27]
	v_pk_mul_f32 v[100:101], v[144:145], v[38:39]
	v_pk_fma_f32 v[92:93], v[146:147], v[28:29], v[92:93]
	v_pk_fma_f32 v[100:101], v[146:147], v[40:41], v[100:101]
	v_pk_mul_f32 v[96:97], v[34:35], v[42:43] op_sel_hi:[1,0]
	v_pk_mul_f32 v[98:99], v[36:37], v[42:43] op_sel_hi:[1,0]
	v_add_f32_e32 v92, v92, v93
	v_add_f32_e32 v100, v100, v101
	v_pk_fma_f32 v[96:97], v[144:145], v[22:23], v[96:97]
	v_pk_fma_f32 v[98:99], v[146:147], v[24:25], v[98:99]
	v_add_f32_dpp v92, v92, v92 row_ror:8 row_mask:0xf bank_mask:0xf bound_ctrl:1
	v_add_f32_dpp v100, v100, v100 row_ror:8 row_mask:0xf bank_mask:0xf bound_ctrl:1
	ds_read_b128 v[0:3], v186 offset:16128
	v_add_f32_dpp v92, v92, v92 row_ror:4 row_mask:0xf bank_mask:0xf bound_ctrl:1
	ds_read_b128 v[4:7], v186 offset:16384
	ds_read_b128 v[8:11], v186 offset:16640
	v_add_f32_dpp v92, v92, v92 row_ror:2 row_mask:0xf bank_mask:0xf bound_ctrl:1
	v_add_f32_dpp v100, v100, v100 row_ror:4 row_mask:0xf bank_mask:0xf bound_ctrl:1
	ds_read_b128 v[12:15], v186 offset:16896
	v_add_f32_dpp v92, v92, v92 row_ror:1 row_mask:0xf bank_mask:0xf bound_ctrl:1
	ds_read_b128 v[16:19], v186 offset:17152
	ds_read_b32 v20, v187 offset:17408
	v_pk_fma_f32 v[144:145], v[30:31], v[92:93], v[96:97] op_sel_hi:[1,0,1]
	v_pk_fma_f32 v[146:147], v[32:33], v[92:93], v[98:99] op_sel_hi:[1,0,1]
	ds_write_b32 v189, v100 offset:2560
	s_waitcnt lgkmcnt(8)
; template <int CTRL> __device__ __forceinline__ float dpp_add(float x) { const int y = __builtin_amdgcn_update_dpp(0, __float_as_int(x), CTRL, 0xf, 0xf, false); return x + __int_as_float(y); }
; __device__ __forceinline__ float row16_sum(float x) { x = dpp_add<0x128>(x); x = dpp_add<0x124>(x); x = dpp_add<0x122>(x); x = dpp_add<0x121>(x); return x; }
; #define LO2(x) __builtin_shufflevector(x, x, 0, 1)
; #define HI2(x) __builtin_shufflevector(x, x, 2, 3)
; template <int DIR> __device__ __forceinline__ void rwkv_scan_dir(const Params& P, unsigned char* lds, int sb, int tid) {
;     ...
;             for (int st = 0; st < SC_CH; ++st) {
;                 const float* rn = rp + (st + 2) * 336;
;                 const f32x4 nw = *(const f32x4*)(rn), nkk = *(const f32x4*)(rn + 64), nkka = *(const f32x4*)(rn + 128), nkm = *(const f32x4*)(rn + 192), nr = *(const f32x4*)(rn + 256);
;                 const float nv = vp[(st + 2) * 336];
;                 f32x2 q = sA * LO2(kk); q = sB * HI2(kk) + q;
;                 float sk = q.x + q.y;
;                 float yy = 0.f;
;                 if (DIR == 1) { f32x2 yq = sA * LO2(r); yq = sB * HI2(r) + yq; yy = yq.x + yq.y; }
;                 sk = row16_sum(sk);
;                 f32x2 tA = LO2(km) * v, tB = HI2(km) * v;
;                 tA = sA * LO2(w) + tA; tB = sB * HI2(w) + tB;
;                 sA = LO2(kka) * sk + tA; sB = HI2(kka) * sk + tB;
;                 if (DIR == 0) { f32x2 yq = sA * LO2(r); yq = sB * HI2(r) + yq; yy = yq.x + yq.y; }
;                 yy = dpp_add<0x128>(yy); yy = dpp_add<0x124>(yy);
;                 yp[st * 64] = yy;
;                 w = w1; kk = kk1; kka = kka1; km = km1; r = r1; v = v1;
;                 w1 = nw; kk1 = nkk; kka1 = nkka; km1 = nkm; r1 = nr; v1 = nv;
	v_pk_mul_f32 v[92:93], v[144:145], v[48:49]
	v_pk_mul_f32 v[102:103], v[144:145], v[60:61]
	v_pk_fma_f32 v[92:93], v[146:147], v[50:51], v[92:93]
	v_pk_fma_f32 v[102:103], v[146:147], v[62:63], v[102:103]
	v_pk_mul_f32 v[96:97], v[56:57], v[64:65] op_sel_hi:[1,0]
	v_pk_mul_f32 v[98:99], v[58:59], v[64:65] op_sel_hi:[1,0]
	v_add_f32_e32 v92, v92, v93
	v_add_f32_e32 v102, v102, v103
	v_pk_fma_f32 v[96:97], v[144:145], v[44:45], v[96:97]
	v_pk_fma_f32 v[98:99], v[146:147], v[46:47], v[98:99]
	v_add_f32_dpp v92, v92, v92 row_ror:8 row_mask:0xf bank_mask:0xf bound_ctrl:1
	v_add_f32_dpp v102, v102, v102 row_ror:8 row_mask:0xf bank_mask:0xf bound_ctrl:1
	ds_read_b128 v[22:25], v186 offset:17472
	v_add_f32_dpp v92, v92, v92 row_ror:4 row_mask:0xf bank_mask:0xf bound_ctrl:1
	ds_read_b128 v[26:29], v186 offset:17728
	ds_read_b128 v[30:33], v186 offset:17984
	v_add_f32_dpp v92, v92, v92 row_ror:2 row_mask:0xf bank_mask:0xf bound_ctrl:1
	v_add_f32_dpp v102, v102, v102 row_ror:4 row_mask:0xf bank_mask:0xf bound_ctrl:1
	ds_read_b128 v[34:37], v186 offset:18240
	v_add_f32_dpp v92, v92, v92 row_ror:1 row_mask:0xf bank_mask:0xf bound_ctrl:1
	ds_read_b128 v[38:41], v186 offset:18496
	ds_read_b32 v42, v187 offset:18752
	v_pk_fma_f32 v[144:145], v[52:53], v[92:93], v[96:97] op_sel_hi:[1,0,1]
	v_pk_fma_f32 v[146:147], v[54:55], v[92:93], v[98:99] op_sel_hi:[1,0,1]
	ds_write_b32 v189, v102 offset:2816
	s_waitcnt lgkmcnt(8)
	v_pk_mul_f32 v[92:93], v[144:145], v[4:5]
	v_pk_mul_f32 v[100:101], v[144:145], v[16:17]
	v_pk_fma_f32 v[92:93], v[146:147], v[6:7], v[92:93]
	v_pk_fma_f32 v[100:101], v[146:147], v[18:19], v[100:101]
	v_pk_mul_f32 v[96:97], v[12:13], v[20:21] op_sel_hi:[1,0]
	v_pk_mul_f32 v[98:99], v[14:15], v[20:21] op_sel_hi:[1,0]
	v_add_f32_e32 v92, v92, v93
	v_add_f32_e32 v100, v100, v101
	v_pk_fma_f32 v[96:97], v[144:145], v[0:1], v[96:97]
	v_pk_fma_f32 v[98:99], v[146:147], v[2:3], v[98:99]
	v_add_f32_dpp v92, v92, v92 row_ror:8 row_mask:0xf bank_mask:0xf bound_ctrl:1
	v_add_f32_dpp v100, v100, v100 row_ror:8 row_mask:0xf bank_mask:0xf bound_ctrl:1
	ds_read_b128 v[44:47], v186 offset:18816
	v_add_f32_dpp v92, v92, v92 row_ror:4 row_mask:0xf bank_mask:0xf bound_ctrl:1
	ds_read_b128 v[48:51], v186 offset:19072
	ds_read_b128 v[52:55], v186 offset:19328
	v_add_f32_dpp v92, v92, v92 row_ror:2 row_mask:0xf bank_mask:0xf bound_ctrl:1
	v_add_f32_dpp v100, v100, v100 row_ror:4 row_mask:0xf bank_mask:0xf bound_ctrl:1
	ds_read_b128 v[56:59], v186 offset:19584
	v_add_f32_dpp v92, v92, v92 row_ror:1 row_mask:0xf bank_mask:0xf bound_ctrl:1
	ds_read_b128 v[60:63], v186 offset:19840
	ds_read_b32 v64, v187 offset:20096
	v_pk_fma_f32 v[144:145], v[8:9], v[92:93], v[96:97] op_sel_hi:[1,0,1]
	v_pk_fma_f32 v[146:147], v[10:11], v[92:93], v[98:99] op_sel_hi:[1,0,1]
	ds_write_b32 v189, v100 offset:3072
	s_waitcnt lgkmcnt(8)
	v_pk_mul_f32 v[92:93], v[144:145], v[26:27]
	v_pk_mul_f32 v[102:103], v[144:145], v[38:39]
	v_pk_fma_f32 v[92:93], v[146:147], v[28:29], v[92:93]
	v_pk_fma_f32 v[102:103], v[146:147], v[40:41], v[102:103]
	v_pk_mul_f32 v[96:97], v[34:35], v[42:43] op_sel_hi:[1,0]
	v_pk_mul_f32 v[98:99], v[36:37], v[42:43] op_sel_hi:[1,0]
	v_add_f32_e32 v92, v92, v93
	v_add_f32_e32 v102, v102, v103
	v_pk_fma_f32 v[96:97], v[144:145], v[22:23], v[96:97]
	v_pk_fma_f32 v[98:99], v[146:147], v[24:25], v[98:99]
	v_add_f32_dpp v92, v92, v92 row_ror:8 row_mask:0xf bank_mask:0xf bound_ctrl:1
	v_add_f32_dpp v102, v102, v102 row_ror:8 row_mask:0xf bank_mask:0xf bound_ctrl:1
	ds_read_b128 v[0:3], v186 offset:20160
	v_add_f32_dpp v92, v92, v92 row_ror:4 row_mask:0xf bank_mask:0xf bound_ctrl:1
	ds_read_b128 v[4:7], v186 offset:20416
	ds_read_b128 v[8:11], v186 offset:20672
	v_add_f32_dpp v92, v92, v92 row_ror:2 row_mask:0xf bank_mask:0xf bound_ctrl:1
	v_add_f32_dpp v102, v102, v102 row_ror:4 row_mask:0xf bank_mask:0xf bound_ctrl:1
	ds_read_b128 v[12:15], v186 offset:20928
	v_add_f32_dpp v92, v92, v92 row_ror:1 row_mask:0xf bank_mask:0xf bound_ctrl:1
	ds_read_b128 v[16:19], v186 offset:21184
	ds_read_b32 v20, v187 offset:21440
	v_pk_fma_f32 v[144:145], v[30:31], v[92:93], v[96:97] op_sel_hi:[1,0,1]
	v_pk_fma_f32 v[146:147], v[32:33], v[92:93], v[98:99] op_sel_hi:[1,0,1]
	ds_write_b32 v189, v102 offset:3328
	s_waitcnt lgkmcnt(8)
	v_pk_mul_f32 v[92:93], v[144:145], v[48:49]
	v_pk_mul_f32 v[100:101], v[144:145], v[60:61]
	v_pk_fma_f32 v[92:93], v[146:147], v[50:51], v[92:93]
	v_pk_fma_f32 v[100:101], v[146:147], v[62:63], v[100:101]
	v_pk_mul_f32 v[96:97], v[56:57], v[64:65] op_sel_hi:[1,0]
	v_pk_mul_f32 v[98:99], v[58:59], v[64:65] op_sel_hi:[1,0]
	v_add_f32_e32 v92, v92, v93
	v_add_f32_e32 v100, v100, v101
	v_pk_fma_f32 v[96:97], v[144:145], v[44:45], v[96:97]
	v_pk_fma_f32 v[98:99], v[146:147], v[46:47], v[98:99]
	v_add_f32_dpp v92, v92, v92 row_ror:8 row_mask:0xf bank_mask:0xf bound_ctrl:1
	v_add_f32_dpp v100, v100, v100 row_ror:8 row_mask:0xf bank_mask:0xf bound_ctrl:1
	s_nop 0
	v_add_f32_dpp v92, v92, v92 row_ror:4 row_mask:0xf bank_mask:0xf bound_ctrl:1
	s_nop 0
	s_nop 0
	v_add_f32_dpp v92, v92, v92 row_ror:2 row_mask:0xf bank_mask:0xf bound_ctrl:1
	v_add_f32_dpp v100, v100, v100 row_ror:4 row_mask:0xf bank_mask:0xf bound_ctrl:1
	s_nop 0
	v_add_f32_dpp v92, v92, v92 row_ror:1 row_mask:0xf bank_mask:0xf bound_ctrl:1
	s_nop 0
	s_nop 0
	v_pk_fma_f32 v[144:145], v[52:53], v[92:93], v[96:97] op_sel_hi:[1,0,1]
	v_pk_fma_f32 v[146:147], v[54:55], v[92:93], v[98:99] op_sel_hi:[1,0,1]
	ds_write_b32 v189, v100 offset:3584
	s_waitcnt lgkmcnt(2)
	v_pk_mul_f32 v[92:93], v[144:145], v[4:5]
	v_pk_mul_f32 v[102:103], v[144:145], v[16:17]
	v_pk_fma_f32 v[92:93], v[146:147], v[6:7], v[92:93]
	v_pk_fma_f32 v[102:103], v[146:147], v[18:19], v[102:103]
	v_pk_mul_f32 v[96:97], v[12:13], v[20:21] op_sel_hi:[1,0]
	v_pk_mul_f32 v[98:99], v[14:15], v[20:21] op_sel_hi:[1,0]
	v_add_f32_e32 v92, v92, v93
	v_add_f32_e32 v102, v102, v103
	v_pk_fma_f32 v[96:97], v[144:145], v[0:1], v[96:97]
	v_pk_fma_f32 v[98:99], v[146:147], v[2:3], v[98:99]
	v_add_f32_dpp v92, v92, v92 row_ror:8 row_mask:0xf bank_mask:0xf bound_ctrl:1
	v_add_f32_dpp v102, v102, v102 row_ror:8 row_mask:0xf bank_mask:0xf bound_ctrl:1
	s_nop 0
	v_add_f32_dpp v92, v92, v92 row_ror:4 row_mask:0xf bank_mask:0xf bound_ctrl:1
	s_nop 0
	s_nop 0
	v_add_f32_dpp v92, v92, v92 row_ror:2 row_mask:0xf bank_mask:0xf bound_ctrl:1
	v_add_f32_dpp v102, v102, v102 row_ror:4 row_mask:0xf bank_mask:0xf bound_ctrl:1
	s_nop 0
	v_add_f32_dpp v92, v92, v92 row_ror:1 row_mask:0xf bank_mask:0xf bound_ctrl:1
	s_nop 0
	s_nop 0
	v_pk_fma_f32 v[144:145], v[8:9], v[92:93], v[96:97] op_sel_hi:[1,0,1]
	v_pk_fma_f32 v[146:147], v[10:11], v[92:93], v[98:99] op_sel_hi:[1,0,1]
	ds_write_b32 v189, v102 offset:3840
	v_add_u32_e32 v85, 1, v162
